# GEMM main loops: each accumulator's two K-halves back to back, plain tile order (no snake)
# baseline (speedup 1.0000x reference)
.LBB0_120:
	s_add_u32 s28, s40, 0xfff80080
	s_addc_u32 s29, s41, -1
	s_add_i32 s54, 0, 0x10000
	s_cmp_eq_u32 s53, 28
	s_cselect_b32 s29, s23, s29
	s_cselect_b32 s28, s22, s28
	s_cselect_b32 s43, s21, s52
	s_cselect_b32 s42, s50, s51
	s_add_i32 s56, 0, 0x14000
	v_add_u32_e32 v142, s54, v212
	v_add_u32_e32 v158, s56, v212
	ds_read_b128 v[130:133], v142
	ds_read_b128 v[134:137], v142 offset:1024
	ds_read_b128 v[138:141], v142 offset:2048
	ds_read_b128 v[142:145], v142 offset:3072
	ds_read_b128 v[146:149], v158
	ds_read_b128 v[150:153], v158 offset:1024
	ds_read_b128 v[154:157], v158 offset:2048
	ds_read_b128 v[158:161], v158 offset:3072
	v_lshl_add_u64 v[204:205], s[40:41], 0, v[184:185]
	s_add_i32 m0, s24, 0xc000
	ds_read_b128 v[162:165], v213
	ds_read_b128 v[166:169], v213 offset:1024
	ds_read_b128 v[170:173], v213 offset:2048
	ds_read_b128 v[174:177], v213 offset:3072
	ds_read_b128 v[188:191], v213 offset:4096
	ds_read_b128 v[192:195], v213 offset:5120
	ds_read_b128 v[196:199], v213 offset:6144
	ds_read_b128 v[200:203], v213 offset:7168
	global_load_lds_dwordx4 v[204:205], off
	v_lshl_add_u64 v[204:205], s[40:41], 0, v[186:187]
	s_add_i32 m0, s24, 0xe000
	s_nop 0
	global_load_lds_dwordx4 v[204:205], off
	s_waitcnt vmcnt(8)
	s_waitcnt lgkmcnt(0)
	s_barrier
	s_setprio 1
	s_waitcnt lgkmcnt(0)
	v_mfma_f32_16x16x32_bf16 v[126:129], v[130:133], v[162:165], v[126:129]
	v_mfma_f32_16x16x32_bf16 v[126:129], v[134:137], v[166:169], v[126:129]
	v_mfma_f32_16x16x32_bf16 v[122:125], v[138:141], v[162:165], v[122:125]
	v_mfma_f32_16x16x32_bf16 v[122:125], v[142:145], v[166:169], v[122:125]
	v_mfma_f32_16x16x32_bf16 v[110:113], v[130:133], v[170:173], v[110:113]
	v_mfma_f32_16x16x32_bf16 v[110:113], v[134:137], v[174:177], v[110:113]
	v_mfma_f32_16x16x32_bf16 v[106:109], v[138:141], v[170:173], v[106:109]
	v_mfma_f32_16x16x32_bf16 v[106:109], v[142:145], v[174:177], v[106:109]
	v_mfma_f32_16x16x32_bf16 v[94:97], v[130:133], v[188:191], v[94:97]
	v_mfma_f32_16x16x32_bf16 v[94:97], v[134:137], v[192:195], v[94:97]
	v_mfma_f32_16x16x32_bf16 v[90:93], v[138:141], v[188:191], v[90:93]
	v_mfma_f32_16x16x32_bf16 v[90:93], v[142:145], v[192:195], v[90:93]
	v_mfma_f32_16x16x32_bf16 v[78:81], v[130:133], v[196:199], v[78:81]
	v_mfma_f32_16x16x32_bf16 v[78:81], v[134:137], v[200:203], v[78:81]
	v_mfma_f32_16x16x32_bf16 v[74:77], v[138:141], v[196:199], v[74:77]
	v_mfma_f32_16x16x32_bf16 v[74:77], v[142:145], v[200:203], v[74:77]
	s_setprio 0
	s_setprio 1
	v_mfma_f32_16x16x32_bf16 v[118:121], v[146:149], v[162:165], v[118:121]
	v_mfma_f32_16x16x32_bf16 v[118:121], v[150:153], v[166:169], v[118:121]
	v_mfma_f32_16x16x32_bf16 v[114:117], v[154:157], v[162:165], v[114:117]
	v_mfma_f32_16x16x32_bf16 v[114:117], v[158:161], v[166:169], v[114:117]
	v_mfma_f32_16x16x32_bf16 v[102:105], v[146:149], v[170:173], v[102:105]
	v_mfma_f32_16x16x32_bf16 v[102:105], v[150:153], v[174:177], v[102:105]
	v_mfma_f32_16x16x32_bf16 v[98:101], v[154:157], v[170:173], v[98:101]
	v_mfma_f32_16x16x32_bf16 v[98:101], v[158:161], v[174:177], v[98:101]
	v_mfma_f32_16x16x32_bf16 v[86:89], v[146:149], v[188:191], v[86:89]
	v_mfma_f32_16x16x32_bf16 v[86:89], v[150:153], v[192:195], v[86:89]
	v_mfma_f32_16x16x32_bf16 v[82:85], v[154:157], v[188:191], v[82:85]
	v_mfma_f32_16x16x32_bf16 v[82:85], v[158:161], v[192:195], v[82:85]
	v_mfma_f32_16x16x32_bf16 v[70:73], v[146:149], v[196:199], v[70:73]
	v_mfma_f32_16x16x32_bf16 v[70:73], v[150:153], v[200:203], v[70:73]
	v_mfma_f32_16x16x32_bf16 v[66:69], v[154:157], v[196:199], v[66:69]
	v_mfma_f32_16x16x32_bf16 v[66:69], v[158:161], v[200:203], v[66:69]
	s_setprio 0
	s_barrier
	s_add_i32 s54, s54, s1
	v_lshl_add_u64 v[204:205], s[42:43], 0, v[32:33]
	s_mov_b32 m0, s54
	ds_read_b128 v[162:165], v213 offset:16384
	ds_read_b128 v[166:169], v213 offset:17408
	ds_read_b128 v[170:173], v213 offset:18432
	ds_read_b128 v[174:177], v213 offset:19456
	ds_read_b128 v[188:191], v213 offset:20480
	ds_read_b128 v[192:195], v213 offset:21504
	ds_read_b128 v[196:199], v213 offset:22528
	ds_read_b128 v[200:203], v213 offset:23552
	global_load_lds_dwordx4 v[204:205], off
	s_add_i32 m0, s54, 0x2000
	s_add_u32 s54, s42, 0x80000
	v_lshl_add_u64 v[206:207], s[42:43], 0, v[182:183]
	s_addc_u32 s55, s43, 0
	s_add_i32 s56, s56, s1
	global_load_lds_dwordx4 v[206:207], off
	v_lshl_add_u64 v[208:209], s[54:55], 0, v[32:33]
	s_mov_b32 m0, s56
	v_lshl_add_u64 v[214:215], s[28:29], 0, v[180:181]
	global_load_lds_dwordx4 v[208:209], off
	v_lshl_add_u64 v[208:209], s[54:55], 0, v[182:183]
	s_add_i32 m0, s56, 0x2000
	s_nop 0
	global_load_lds_dwordx4 v[208:209], off
	v_lshl_add_u64 v[208:209], s[28:29], 0, v[178:179]
	s_mov_b32 m0, s24
	s_nop 0
	global_load_lds_dwordx4 v[208:209], off
	s_mov_b32 m0, s25
	s_nop 0
	global_load_lds_dwordx4 v[214:215], off
	s_waitcnt vmcnt(8)
	s_waitcnt lgkmcnt(0)
	s_barrier
	s_setprio 1
	s_waitcnt lgkmcnt(0)
	v_mfma_f32_16x16x32_bf16 v[62:65], v[130:133], v[162:165], v[62:65]
	v_mfma_f32_16x16x32_bf16 v[62:65], v[134:137], v[166:169], v[62:65]
	v_mfma_f32_16x16x32_bf16 v[58:61], v[138:141], v[162:165], v[58:61]
	v_mfma_f32_16x16x32_bf16 v[58:61], v[142:145], v[166:169], v[58:61]
	v_mfma_f32_16x16x32_bf16 v[46:49], v[130:133], v[170:173], v[46:49]
	v_mfma_f32_16x16x32_bf16 v[46:49], v[134:137], v[174:177], v[46:49]
	v_mfma_f32_16x16x32_bf16 v[42:45], v[138:141], v[170:173], v[42:45]
	v_mfma_f32_16x16x32_bf16 v[42:45], v[142:145], v[174:177], v[42:45]
	v_mfma_f32_16x16x32_bf16 v[28:31], v[130:133], v[188:191], v[28:31]
	v_mfma_f32_16x16x32_bf16 v[28:31], v[134:137], v[192:195], v[28:31]
	v_mfma_f32_16x16x32_bf16 v[24:27], v[138:141], v[188:191], v[24:27]
	v_mfma_f32_16x16x32_bf16 v[24:27], v[142:145], v[192:195], v[24:27]
	v_mfma_f32_16x16x32_bf16 v[12:15], v[130:133], v[196:199], v[12:15]
	v_mfma_f32_16x16x32_bf16 v[12:15], v[134:137], v[200:203], v[12:15]
	v_mfma_f32_16x16x32_bf16 v[8:11], v[138:141], v[196:199], v[8:11]
	v_mfma_f32_16x16x32_bf16 v[8:11], v[142:145], v[200:203], v[8:11]
	s_setprio 0
	s_setprio 1
	v_mfma_f32_16x16x32_bf16 v[54:57], v[146:149], v[162:165], v[54:57]
	v_mfma_f32_16x16x32_bf16 v[54:57], v[150:153], v[166:169], v[54:57]
	v_mfma_f32_16x16x32_bf16 v[50:53], v[154:157], v[162:165], v[50:53]
	v_mfma_f32_16x16x32_bf16 v[50:53], v[158:161], v[166:169], v[50:53]
	v_mfma_f32_16x16x32_bf16 v[38:41], v[146:149], v[170:173], v[38:41]
	v_mfma_f32_16x16x32_bf16 v[38:41], v[150:153], v[174:177], v[38:41]
	v_mfma_f32_16x16x32_bf16 v[34:37], v[154:157], v[170:173], v[34:37]
	v_mfma_f32_16x16x32_bf16 v[34:37], v[158:161], v[174:177], v[34:37]
	v_mfma_f32_16x16x32_bf16 v[20:23], v[146:149], v[188:191], v[20:23]
	v_mfma_f32_16x16x32_bf16 v[20:23], v[150:153], v[192:195], v[20:23]
	v_mfma_f32_16x16x32_bf16 v[16:19], v[154:157], v[188:191], v[16:19]
	v_mfma_f32_16x16x32_bf16 v[16:19], v[158:161], v[192:195], v[16:19]
	v_mfma_f32_16x16x32_bf16 v[4:7], v[146:149], v[196:199], v[4:7]
	v_mfma_f32_16x16x32_bf16 v[4:7], v[150:153], v[200:203], v[4:7]
	v_mfma_f32_16x16x32_bf16 v[0:3], v[154:157], v[196:199], v[0:3]
	v_mfma_f32_16x16x32_bf16 v[0:3], v[158:161], v[200:203], v[0:3]
	s_setprio 0
	s_barrier
	s_add_i32 s54, 0, 0x18000
	s_add_i32 s55, 0, 0x1c000
	v_add_u32_e32 v142, s54, v212
	v_add_u32_e32 v158, s55, v212
	ds_read_b128 v[130:133], v142
	ds_read_b128 v[134:137], v142 offset:1024
	ds_read_b128 v[138:141], v142 offset:2048
	ds_read_b128 v[142:145], v142 offset:3072
	ds_read_b128 v[146:149], v158
	ds_read_b128 v[150:153], v158 offset:1024
	ds_read_b128 v[154:157], v158 offset:2048
	ds_read_b128 v[158:161], v158 offset:3072
	s_add_u32 s28, s28, 0x80000
	s_addc_u32 s29, s29, 0
	s_mov_b32 m0, s33
	v_lshl_add_u64 v[216:217], s[28:29], 0, v[178:179]
	ds_read_b128 v[162:165], v213 offset:32768
	ds_read_b128 v[166:169], v213 offset:33792
	ds_read_b128 v[170:173], v213 offset:34816
	ds_read_b128 v[174:177], v213 offset:35840
	ds_read_b128 v[188:191], v213 offset:36864
	ds_read_b128 v[192:195], v213 offset:37888
	ds_read_b128 v[196:199], v213 offset:38912
	ds_read_b128 v[200:203], v213 offset:39936
	global_load_lds_dwordx4 v[216:217], off
	v_lshl_add_u64 v[216:217], s[28:29], 0, v[180:181]
	s_mov_b32 m0, s36
	s_nop 0
	global_load_lds_dwordx4 v[216:217], off
	s_waitcnt vmcnt(8)
	s_waitcnt lgkmcnt(0)
	s_barrier
	s_setprio 1
	s_waitcnt lgkmcnt(0)
	v_mfma_f32_16x16x32_bf16 v[126:129], v[130:133], v[162:165], v[126:129]
	v_mfma_f32_16x16x32_bf16 v[126:129], v[134:137], v[166:169], v[126:129]
	v_mfma_f32_16x16x32_bf16 v[122:125], v[138:141], v[162:165], v[122:125]
	v_mfma_f32_16x16x32_bf16 v[122:125], v[142:145], v[166:169], v[122:125]
	v_mfma_f32_16x16x32_bf16 v[110:113], v[130:133], v[170:173], v[110:113]
	v_mfma_f32_16x16x32_bf16 v[110:113], v[134:137], v[174:177], v[110:113]
	v_mfma_f32_16x16x32_bf16 v[106:109], v[138:141], v[170:173], v[106:109]
	v_mfma_f32_16x16x32_bf16 v[106:109], v[142:145], v[174:177], v[106:109]
	v_mfma_f32_16x16x32_bf16 v[94:97], v[130:133], v[188:191], v[94:97]
	v_mfma_f32_16x16x32_bf16 v[94:97], v[134:137], v[192:195], v[94:97]
	v_mfma_f32_16x16x32_bf16 v[90:93], v[138:141], v[188:191], v[90:93]
	v_mfma_f32_16x16x32_bf16 v[90:93], v[142:145], v[192:195], v[90:93]
	v_mfma_f32_16x16x32_bf16 v[78:81], v[130:133], v[196:199], v[78:81]
	v_mfma_f32_16x16x32_bf16 v[78:81], v[134:137], v[200:203], v[78:81]
	v_mfma_f32_16x16x32_bf16 v[74:77], v[138:141], v[196:199], v[74:77]
	v_mfma_f32_16x16x32_bf16 v[74:77], v[142:145], v[200:203], v[74:77]
	s_setprio 0
	s_setprio 1
	v_mfma_f32_16x16x32_bf16 v[118:121], v[146:149], v[162:165], v[118:121]
	v_mfma_f32_16x16x32_bf16 v[118:121], v[150:153], v[166:169], v[118:121]
	v_mfma_f32_16x16x32_bf16 v[114:117], v[154:157], v[162:165], v[114:117]
	v_mfma_f32_16x16x32_bf16 v[114:117], v[158:161], v[166:169], v[114:117]
	v_mfma_f32_16x16x32_bf16 v[102:105], v[146:149], v[170:173], v[102:105]
	v_mfma_f32_16x16x32_bf16 v[102:105], v[150:153], v[174:177], v[102:105]
	v_mfma_f32_16x16x32_bf16 v[98:101], v[154:157], v[170:173], v[98:101]
	v_mfma_f32_16x16x32_bf16 v[98:101], v[158:161], v[174:177], v[98:101]
	v_mfma_f32_16x16x32_bf16 v[86:89], v[146:149], v[188:191], v[86:89]
	v_mfma_f32_16x16x32_bf16 v[86:89], v[150:153], v[192:195], v[86:89]
	v_mfma_f32_16x16x32_bf16 v[82:85], v[154:157], v[188:191], v[82:85]
	v_mfma_f32_16x16x32_bf16 v[82:85], v[158:161], v[192:195], v[82:85]
	v_mfma_f32_16x16x32_bf16 v[70:73], v[146:149], v[196:199], v[70:73]
	v_mfma_f32_16x16x32_bf16 v[70:73], v[150:153], v[200:203], v[70:73]
	v_mfma_f32_16x16x32_bf16 v[66:69], v[154:157], v[196:199], v[66:69]
	v_mfma_f32_16x16x32_bf16 v[66:69], v[158:161], v[200:203], v[66:69]
	s_setprio 0
	s_barrier
	s_add_i32 s28, s54, s1
	v_lshl_add_u64 v[204:205], v[204:205], 0, s[34:35]
	s_mov_b32 m0, s28
	ds_read_b128 v[162:165], v213 offset:49152
	ds_read_b128 v[166:169], v213 offset:50176
	ds_read_b128 v[170:173], v213 offset:51200
	ds_read_b128 v[174:177], v213 offset:52224
	ds_read_b128 v[188:191], v213 offset:53248
	ds_read_b128 v[192:195], v213 offset:54272
	ds_read_b128 v[196:199], v213 offset:55296
	ds_read_b128 v[200:203], v213 offset:56320
	global_load_lds_dwordx4 v[204:205], off
	s_add_i32 m0, s28, 0x2000
	s_add_u32 s28, s42, 0x80080
	v_lshl_add_u64 v[204:205], v[206:207], 0, s[34:35]
	s_addc_u32 s29, s43, 0
	s_add_i32 s42, s55, s1
	global_load_lds_dwordx4 v[204:205], off
	v_lshl_add_u64 v[204:205], s[28:29], 0, v[32:33]
	s_mov_b32 m0, s42
	s_nop 0
	global_load_lds_dwordx4 v[204:205], off
	v_lshl_add_u64 v[204:205], s[28:29], 0, v[182:183]
	s_add_i32 m0, s42, 0x2000
	s_nop 0
	global_load_lds_dwordx4 v[204:205], off
	v_lshl_add_u64 v[204:205], v[208:209], 0, s[34:35]
	s_mov_b32 m0, s44
	s_nop 0
	global_load_lds_dwordx4 v[204:205], off
	v_lshl_add_u64 v[204:205], v[214:215], 0, s[34:35]
	s_mov_b32 m0, s45
	s_nop 0
	global_load_lds_dwordx4 v[204:205], off
	s_waitcnt vmcnt(8)
	s_waitcnt lgkmcnt(0)
	s_barrier
	s_setprio 1
	s_waitcnt lgkmcnt(0)
	v_mfma_f32_16x16x32_bf16 v[62:65], v[130:133], v[162:165], v[62:65]
	v_mfma_f32_16x16x32_bf16 v[62:65], v[134:137], v[166:169], v[62:65]
	v_mfma_f32_16x16x32_bf16 v[58:61], v[138:141], v[162:165], v[58:61]
	v_mfma_f32_16x16x32_bf16 v[58:61], v[142:145], v[166:169], v[58:61]
	v_mfma_f32_16x16x32_bf16 v[46:49], v[130:133], v[170:173], v[46:49]
	v_mfma_f32_16x16x32_bf16 v[46:49], v[134:137], v[174:177], v[46:49]
	v_mfma_f32_16x16x32_bf16 v[42:45], v[138:141], v[170:173], v[42:45]
	v_mfma_f32_16x16x32_bf16 v[42:45], v[142:145], v[174:177], v[42:45]
	v_mfma_f32_16x16x32_bf16 v[28:31], v[130:133], v[188:191], v[28:31]
	v_mfma_f32_16x16x32_bf16 v[28:31], v[134:137], v[192:195], v[28:31]
	v_mfma_f32_16x16x32_bf16 v[24:27], v[138:141], v[188:191], v[24:27]
	v_mfma_f32_16x16x32_bf16 v[24:27], v[142:145], v[192:195], v[24:27]
	v_mfma_f32_16x16x32_bf16 v[12:15], v[130:133], v[196:199], v[12:15]
	v_mfma_f32_16x16x32_bf16 v[12:15], v[134:137], v[200:203], v[12:15]
	v_mfma_f32_16x16x32_bf16 v[8:11], v[138:141], v[196:199], v[8:11]
	v_mfma_f32_16x16x32_bf16 v[8:11], v[142:145], v[200:203], v[8:11]
	s_setprio 0
	s_setprio 1
	v_mfma_f32_16x16x32_bf16 v[54:57], v[146:149], v[162:165], v[54:57]
	v_mfma_f32_16x16x32_bf16 v[54:57], v[150:153], v[166:169], v[54:57]
	v_mfma_f32_16x16x32_bf16 v[50:53], v[154:157], v[162:165], v[50:53]
	v_mfma_f32_16x16x32_bf16 v[50:53], v[158:161], v[166:169], v[50:53]
	v_mfma_f32_16x16x32_bf16 v[38:41], v[146:149], v[170:173], v[38:41]
	v_mfma_f32_16x16x32_bf16 v[38:41], v[150:153], v[174:177], v[38:41]
	v_mfma_f32_16x16x32_bf16 v[34:37], v[154:157], v[170:173], v[34:37]
	v_mfma_f32_16x16x32_bf16 v[34:37], v[158:161], v[174:177], v[34:37]
	v_mfma_f32_16x16x32_bf16 v[20:23], v[146:149], v[188:191], v[20:23]
	v_mfma_f32_16x16x32_bf16 v[20:23], v[150:153], v[192:195], v[20:23]
	v_mfma_f32_16x16x32_bf16 v[16:19], v[154:157], v[188:191], v[16:19]
	v_mfma_f32_16x16x32_bf16 v[16:19], v[158:161], v[192:195], v[16:19]
	v_mfma_f32_16x16x32_bf16 v[4:7], v[146:149], v[196:199], v[4:7]
	v_mfma_f32_16x16x32_bf16 v[4:7], v[150:153], v[200:203], v[4:7]
	v_mfma_f32_16x16x32_bf16 v[0:3], v[154:157], v[196:199], v[0:3]
	v_mfma_f32_16x16x32_bf16 v[0:3], v[158:161], v[200:203], v[0:3]
	s_setprio 0
	s_barrier
	s_add_i32 s53, s53, 2
	s_add_u32 s40, s40, 0x100
	s_addc_u32 s41, s41, 0
	s_add_u32 s51, s51, 0x100
	s_addc_u32 s52, s52, 0
	s_cmp_gt_u32 s53, 29
	s_cbranch_scc0 .LBB0_120
	s_and_b64 vcc, exec, s[18:19]
	s_cbranch_vccz .LBB0_123
	s_barrier

.LBB0_685:
	s_add_u32 s28, s16, s40
	s_addc_u32 s29, s17, s41
	s_add_u32 s28, s28, 0x100
	s_addc_u32 s29, s29, 0
	s_add_u32 s42, s52, s40
	s_addc_u32 s43, s53, s41
	s_add_i32 s56, 0, 0x10000
	s_cmpk_eq_i32 s40, 0xf00
	s_cselect_b32 s29, s39, s29
	s_cselect_b32 s28, s38, s28
	s_cselect_b32 s43, s23, s43
	s_cselect_b32 s42, s54, s42
	s_add_i32 s58, 0, 0x14000
	v_add_u32_e32 v146, s56, v190
	v_add_u32_e32 v162, s58, v190
	ds_read_b128 v[134:137], v146
	ds_read_b128 v[138:141], v146 offset:1024
	ds_read_b128 v[142:145], v146 offset:2048
	ds_read_b128 v[146:149], v146 offset:3072
	ds_read_b128 v[150:153], v162
	ds_read_b128 v[154:157], v162 offset:1024
	ds_read_b128 v[158:161], v162 offset:2048
	ds_read_b128 v[162:165], v162 offset:3072
	v_lshl_add_u64 v[212:213], v[130:131], 0, s[40:41]
	s_add_i32 m0, s24, 0xc000
	ds_read_b128 v[166:169], v191
	ds_read_b128 v[180:183], v191 offset:1024
	ds_read_b128 v[184:187], v191 offset:2048
	ds_read_b128 v[192:195], v191 offset:3072
	ds_read_b128 v[196:199], v191 offset:4096
	ds_read_b128 v[200:203], v191 offset:5120
	ds_read_b128 v[204:207], v191 offset:6144
	ds_read_b128 v[208:211], v191 offset:7168
	global_load_lds_dwordx4 v[212:213], off
	v_lshl_add_u64 v[212:213], v[132:133], 0, s[40:41]
	s_add_i32 m0, s24, 0xe000
	s_nop 0
	global_load_lds_dwordx4 v[212:213], off
	s_waitcnt vmcnt(8)
	s_waitcnt lgkmcnt(0)
	s_barrier
	s_setprio 1
	s_waitcnt lgkmcnt(0)
	v_mfma_f32_16x16x32_bf16 v[82:85], v[134:137], v[166:169], v[82:85]
	v_mfma_f32_16x16x32_bf16 v[82:85], v[138:141], v[180:183], v[82:85]
	v_mfma_f32_16x16x32_bf16 v[78:81], v[142:145], v[166:169], v[78:81]
	v_mfma_f32_16x16x32_bf16 v[78:81], v[146:149], v[180:183], v[78:81]
	v_mfma_f32_16x16x32_bf16 v[74:77], v[134:137], v[184:187], v[74:77]
	v_mfma_f32_16x16x32_bf16 v[74:77], v[138:141], v[192:195], v[74:77]
	v_mfma_f32_16x16x32_bf16 v[70:73], v[142:145], v[184:187], v[70:73]
	v_mfma_f32_16x16x32_bf16 v[70:73], v[146:149], v[192:195], v[70:73]
	v_mfma_f32_16x16x32_bf16 v[66:69], v[134:137], v[196:199], v[66:69]
	v_mfma_f32_16x16x32_bf16 v[66:69], v[138:141], v[200:203], v[66:69]
	v_mfma_f32_16x16x32_bf16 v[62:65], v[142:145], v[196:199], v[62:65]
	v_mfma_f32_16x16x32_bf16 v[62:65], v[146:149], v[200:203], v[62:65]
	v_mfma_f32_16x16x32_bf16 v[58:61], v[134:137], v[204:207], v[58:61]
	v_mfma_f32_16x16x32_bf16 v[58:61], v[138:141], v[208:211], v[58:61]
	v_mfma_f32_16x16x32_bf16 v[54:57], v[142:145], v[204:207], v[54:57]
	v_mfma_f32_16x16x32_bf16 v[54:57], v[146:149], v[208:211], v[54:57]
	s_setprio 0
	s_setprio 1
	v_mfma_f32_16x16x32_bf16 v[50:53], v[150:153], v[166:169], v[50:53]
	v_mfma_f32_16x16x32_bf16 v[50:53], v[154:157], v[180:183], v[50:53]
	v_mfma_f32_16x16x32_bf16 v[46:49], v[158:161], v[166:169], v[46:49]
	v_mfma_f32_16x16x32_bf16 v[46:49], v[162:165], v[180:183], v[46:49]
	v_mfma_f32_16x16x32_bf16 v[42:45], v[150:153], v[184:187], v[42:45]
	v_mfma_f32_16x16x32_bf16 v[42:45], v[154:157], v[192:195], v[42:45]
	v_mfma_f32_16x16x32_bf16 v[38:41], v[158:161], v[184:187], v[38:41]
	v_mfma_f32_16x16x32_bf16 v[38:41], v[162:165], v[192:195], v[38:41]
	v_mfma_f32_16x16x32_bf16 v[34:37], v[150:153], v[196:199], v[34:37]
	v_mfma_f32_16x16x32_bf16 v[34:37], v[154:157], v[200:203], v[34:37]
	v_mfma_f32_16x16x32_bf16 v[28:31], v[158:161], v[196:199], v[28:31]
	v_mfma_f32_16x16x32_bf16 v[28:31], v[162:165], v[200:203], v[28:31]
	v_mfma_f32_16x16x32_bf16 v[24:27], v[150:153], v[204:207], v[24:27]
	v_mfma_f32_16x16x32_bf16 v[24:27], v[154:157], v[208:211], v[24:27]
	v_mfma_f32_16x16x32_bf16 v[20:23], v[158:161], v[204:207], v[20:23]
	v_mfma_f32_16x16x32_bf16 v[20:23], v[162:165], v[208:211], v[20:23]
	s_setprio 0
	s_barrier
	s_add_i32 s56, s56, s13
	v_lshl_add_u64 v[212:213], s[42:43], 0, v[32:33]
	s_mov_b32 m0, s56
	ds_read_b128 v[166:169], v191 offset:16384
	ds_read_b128 v[180:183], v191 offset:17408
	ds_read_b128 v[184:187], v191 offset:18432
	ds_read_b128 v[192:195], v191 offset:19456
	ds_read_b128 v[196:199], v191 offset:20480
	ds_read_b128 v[200:203], v191 offset:21504
	ds_read_b128 v[204:207], v191 offset:22528
	ds_read_b128 v[208:211], v191 offset:23552
	global_load_lds_dwordx4 v[212:213], off
	s_add_i32 m0, s56, 0x2000
	s_add_u32 s56, s42, 0x80000
	v_lshl_add_u64 v[214:215], s[42:43], 0, v[174:175]
	s_addc_u32 s57, s43, 0
	s_add_i32 s58, s58, s13
	global_load_lds_dwordx4 v[214:215], off
	v_lshl_add_u64 v[216:217], s[56:57], 0, v[32:33]
	s_mov_b32 m0, s58
	v_lshl_add_u64 v[220:221], s[28:29], 0, v[172:173]
	global_load_lds_dwordx4 v[216:217], off
	v_lshl_add_u64 v[216:217], s[56:57], 0, v[174:175]
	s_add_i32 m0, s58, 0x2000
	s_nop 0
	global_load_lds_dwordx4 v[216:217], off
	v_lshl_add_u64 v[216:217], s[28:29], 0, v[170:171]
	s_mov_b32 m0, s24
	s_nop 0
	global_load_lds_dwordx4 v[216:217], off
	s_mov_b32 m0, s25
	s_nop 0
	global_load_lds_dwordx4 v[220:221], off
	s_waitcnt vmcnt(8)
	s_waitcnt lgkmcnt(0)
	s_barrier
	s_setprio 1
	s_waitcnt lgkmcnt(0)
	v_mfma_f32_16x16x32_bf16 v[16:19], v[134:137], v[166:169], v[16:19]
	v_mfma_f32_16x16x32_bf16 v[16:19], v[138:141], v[180:183], v[16:19]
	v_mfma_f32_16x16x32_bf16 v[12:15], v[142:145], v[166:169], v[12:15]
	v_mfma_f32_16x16x32_bf16 v[12:15], v[146:149], v[180:183], v[12:15]
	v_mfma_f32_16x16x32_bf16 v[8:11], v[134:137], v[184:187], v[8:11]
	v_mfma_f32_16x16x32_bf16 v[8:11], v[138:141], v[192:195], v[8:11]
	v_mfma_f32_16x16x32_bf16 v[4:7], v[142:145], v[184:187], v[4:7]
	v_mfma_f32_16x16x32_bf16 v[4:7], v[146:149], v[192:195], v[4:7]
	v_mfma_f32_16x16x32_bf16 v[0:3], v[134:137], v[196:199], v[0:3]
	v_mfma_f32_16x16x32_bf16 v[0:3], v[138:141], v[200:203], v[0:3]
	v_mfma_f32_16x16x32_bf16 v[86:89], v[142:145], v[196:199], v[86:89]
	v_mfma_f32_16x16x32_bf16 v[86:89], v[146:149], v[200:203], v[86:89]
	v_mfma_f32_16x16x32_bf16 v[90:93], v[134:137], v[204:207], v[90:93]
	v_mfma_f32_16x16x32_bf16 v[90:93], v[138:141], v[208:211], v[90:93]
	v_mfma_f32_16x16x32_bf16 v[94:97], v[142:145], v[204:207], v[94:97]
	v_mfma_f32_16x16x32_bf16 v[94:97], v[146:149], v[208:211], v[94:97]
	s_setprio 0
	s_setprio 1
	v_mfma_f32_16x16x32_bf16 v[98:101], v[150:153], v[166:169], v[98:101]
	v_mfma_f32_16x16x32_bf16 v[98:101], v[154:157], v[180:183], v[98:101]
	v_mfma_f32_16x16x32_bf16 v[102:105], v[158:161], v[166:169], v[102:105]
	v_mfma_f32_16x16x32_bf16 v[102:105], v[162:165], v[180:183], v[102:105]
	v_mfma_f32_16x16x32_bf16 v[106:109], v[150:153], v[184:187], v[106:109]
	v_mfma_f32_16x16x32_bf16 v[106:109], v[154:157], v[192:195], v[106:109]
	v_mfma_f32_16x16x32_bf16 v[110:113], v[158:161], v[184:187], v[110:113]
	v_mfma_f32_16x16x32_bf16 v[110:113], v[162:165], v[192:195], v[110:113]
	v_mfma_f32_16x16x32_bf16 v[114:117], v[150:153], v[196:199], v[114:117]
	v_mfma_f32_16x16x32_bf16 v[114:117], v[154:157], v[200:203], v[114:117]
	v_mfma_f32_16x16x32_bf16 v[118:121], v[158:161], v[196:199], v[118:121]
	v_mfma_f32_16x16x32_bf16 v[118:121], v[162:165], v[200:203], v[118:121]
	v_mfma_f32_16x16x32_bf16 v[122:125], v[150:153], v[204:207], v[122:125]
	v_mfma_f32_16x16x32_bf16 v[122:125], v[154:157], v[208:211], v[122:125]
	v_mfma_f32_16x16x32_bf16 v[126:129], v[158:161], v[204:207], v[126:129]
	v_mfma_f32_16x16x32_bf16 v[126:129], v[162:165], v[208:211], v[126:129]
	s_setprio 0
	s_barrier
	s_add_i32 s56, 0, 0x18000
	s_add_i32 s57, 0, 0x1c000
	v_add_u32_e32 v146, s56, v190
	v_add_u32_e32 v162, s57, v190
	ds_read_b128 v[134:137], v146
	ds_read_b128 v[138:141], v146 offset:1024
	ds_read_b128 v[142:145], v146 offset:2048
	ds_read_b128 v[146:149], v146 offset:3072
	ds_read_b128 v[150:153], v162
	ds_read_b128 v[154:157], v162 offset:1024
	ds_read_b128 v[158:161], v162 offset:2048
	ds_read_b128 v[162:165], v162 offset:3072
	s_add_u32 s28, s28, 0x80000
	s_addc_u32 s29, s29, 0
	s_mov_b32 m0, s33
	v_lshl_add_u64 v[222:223], s[28:29], 0, v[170:171]
	ds_read_b128 v[166:169], v191 offset:32768
	ds_read_b128 v[180:183], v191 offset:33792
	ds_read_b128 v[184:187], v191 offset:34816
	ds_read_b128 v[192:195], v191 offset:35840
	ds_read_b128 v[196:199], v191 offset:36864
	ds_read_b128 v[200:203], v191 offset:37888
	ds_read_b128 v[204:207], v191 offset:38912
	ds_read_b128 v[208:211], v191 offset:39936
	global_load_lds_dwordx4 v[222:223], off
	v_lshl_add_u64 v[222:223], s[28:29], 0, v[172:173]
	s_mov_b32 m0, s36
	s_nop 0
	global_load_lds_dwordx4 v[222:223], off
	s_waitcnt vmcnt(8)
	s_waitcnt lgkmcnt(0)
	s_barrier
	s_setprio 1
	s_waitcnt lgkmcnt(0)
	v_mfma_f32_16x16x32_bf16 v[82:85], v[134:137], v[166:169], v[82:85]
	v_mfma_f32_16x16x32_bf16 v[82:85], v[138:141], v[180:183], v[82:85]
	v_mfma_f32_16x16x32_bf16 v[78:81], v[142:145], v[166:169], v[78:81]
	v_mfma_f32_16x16x32_bf16 v[78:81], v[146:149], v[180:183], v[78:81]
	v_mfma_f32_16x16x32_bf16 v[74:77], v[134:137], v[184:187], v[74:77]
	v_mfma_f32_16x16x32_bf16 v[74:77], v[138:141], v[192:195], v[74:77]
	v_mfma_f32_16x16x32_bf16 v[70:73], v[142:145], v[184:187], v[70:73]
	v_mfma_f32_16x16x32_bf16 v[70:73], v[146:149], v[192:195], v[70:73]
	v_mfma_f32_16x16x32_bf16 v[66:69], v[134:137], v[196:199], v[66:69]
	v_mfma_f32_16x16x32_bf16 v[66:69], v[138:141], v[200:203], v[66:69]
	v_mfma_f32_16x16x32_bf16 v[62:65], v[142:145], v[196:199], v[62:65]
	v_mfma_f32_16x16x32_bf16 v[62:65], v[146:149], v[200:203], v[62:65]
	v_mfma_f32_16x16x32_bf16 v[58:61], v[134:137], v[204:207], v[58:61]
	v_mfma_f32_16x16x32_bf16 v[58:61], v[138:141], v[208:211], v[58:61]
	v_mfma_f32_16x16x32_bf16 v[54:57], v[142:145], v[204:207], v[54:57]
	v_mfma_f32_16x16x32_bf16 v[54:57], v[146:149], v[208:211], v[54:57]
	s_setprio 0
	s_setprio 1
	v_mfma_f32_16x16x32_bf16 v[50:53], v[150:153], v[166:169], v[50:53]
	v_mfma_f32_16x16x32_bf16 v[50:53], v[154:157], v[180:183], v[50:53]
	v_mfma_f32_16x16x32_bf16 v[46:49], v[158:161], v[166:169], v[46:49]
	v_mfma_f32_16x16x32_bf16 v[46:49], v[162:165], v[180:183], v[46:49]
	v_mfma_f32_16x16x32_bf16 v[42:45], v[150:153], v[184:187], v[42:45]
	v_mfma_f32_16x16x32_bf16 v[42:45], v[154:157], v[192:195], v[42:45]
	v_mfma_f32_16x16x32_bf16 v[38:41], v[158:161], v[184:187], v[38:41]
	v_mfma_f32_16x16x32_bf16 v[38:41], v[162:165], v[192:195], v[38:41]
	v_mfma_f32_16x16x32_bf16 v[34:37], v[150:153], v[196:199], v[34:37]
	v_mfma_f32_16x16x32_bf16 v[34:37], v[154:157], v[200:203], v[34:37]
	v_mfma_f32_16x16x32_bf16 v[28:31], v[158:161], v[196:199], v[28:31]
	v_mfma_f32_16x16x32_bf16 v[28:31], v[162:165], v[200:203], v[28:31]
	v_mfma_f32_16x16x32_bf16 v[24:27], v[150:153], v[204:207], v[24:27]
	v_mfma_f32_16x16x32_bf16 v[24:27], v[154:157], v[208:211], v[24:27]
	v_mfma_f32_16x16x32_bf16 v[20:23], v[158:161], v[204:207], v[20:23]
	v_mfma_f32_16x16x32_bf16 v[20:23], v[162:165], v[208:211], v[20:23]
	s_setprio 0
	s_barrier
	s_add_i32 s28, s56, s13
	v_lshl_add_u64 v[212:213], v[212:213], 0, s[34:35]
	s_mov_b32 m0, s28
	ds_read_b128 v[166:169], v191 offset:49152
	ds_read_b128 v[180:183], v191 offset:50176
	ds_read_b128 v[184:187], v191 offset:51200
	ds_read_b128 v[192:195], v191 offset:52224
	ds_read_b128 v[196:199], v191 offset:53248
	ds_read_b128 v[200:203], v191 offset:54272
	ds_read_b128 v[204:207], v191 offset:55296
	ds_read_b128 v[208:211], v191 offset:56320
	global_load_lds_dwordx4 v[212:213], off
	s_add_i32 m0, s28, 0x2000
	s_add_u32 s28, s42, 0x80080
	v_lshl_add_u64 v[212:213], v[214:215], 0, s[34:35]
	s_addc_u32 s29, s43, 0
	s_add_i32 s42, s57, s13
	global_load_lds_dwordx4 v[212:213], off
	v_lshl_add_u64 v[212:213], s[28:29], 0, v[32:33]
	s_mov_b32 m0, s42
	s_nop 0
	global_load_lds_dwordx4 v[212:213], off
	v_lshl_add_u64 v[212:213], s[28:29], 0, v[174:175]
	s_add_i32 m0, s42, 0x2000
	s_nop 0
	global_load_lds_dwordx4 v[212:213], off
	v_lshl_add_u64 v[212:213], v[216:217], 0, s[34:35]
	s_mov_b32 m0, s45
	s_nop 0
	global_load_lds_dwordx4 v[212:213], off
	v_lshl_add_u64 v[212:213], v[220:221], 0, s[34:35]
	s_mov_b32 m0, s46
	s_nop 0
	global_load_lds_dwordx4 v[212:213], off
	s_waitcnt vmcnt(8)
	s_waitcnt lgkmcnt(0)
	s_barrier
	s_setprio 1
	s_waitcnt lgkmcnt(0)
	v_mfma_f32_16x16x32_bf16 v[16:19], v[134:137], v[166:169], v[16:19]
	v_mfma_f32_16x16x32_bf16 v[16:19], v[138:141], v[180:183], v[16:19]
	v_mfma_f32_16x16x32_bf16 v[12:15], v[142:145], v[166:169], v[12:15]
	v_mfma_f32_16x16x32_bf16 v[12:15], v[146:149], v[180:183], v[12:15]
	v_mfma_f32_16x16x32_bf16 v[8:11], v[134:137], v[184:187], v[8:11]
	v_mfma_f32_16x16x32_bf16 v[8:11], v[138:141], v[192:195], v[8:11]
	v_mfma_f32_16x16x32_bf16 v[4:7], v[142:145], v[184:187], v[4:7]
	v_mfma_f32_16x16x32_bf16 v[4:7], v[146:149], v[192:195], v[4:7]
	v_mfma_f32_16x16x32_bf16 v[0:3], v[134:137], v[196:199], v[0:3]
	v_mfma_f32_16x16x32_bf16 v[0:3], v[138:141], v[200:203], v[0:3]
	v_mfma_f32_16x16x32_bf16 v[86:89], v[142:145], v[196:199], v[86:89]
	v_mfma_f32_16x16x32_bf16 v[86:89], v[146:149], v[200:203], v[86:89]
	v_mfma_f32_16x16x32_bf16 v[90:93], v[134:137], v[204:207], v[90:93]
	v_mfma_f32_16x16x32_bf16 v[90:93], v[138:141], v[208:211], v[90:93]
	v_mfma_f32_16x16x32_bf16 v[94:97], v[142:145], v[204:207], v[94:97]
	v_mfma_f32_16x16x32_bf16 v[94:97], v[146:149], v[208:211], v[94:97]
	s_setprio 0
	s_setprio 1
	v_mfma_f32_16x16x32_bf16 v[98:101], v[150:153], v[166:169], v[98:101]
	v_mfma_f32_16x16x32_bf16 v[98:101], v[154:157], v[180:183], v[98:101]
	v_mfma_f32_16x16x32_bf16 v[102:105], v[158:161], v[166:169], v[102:105]
	v_mfma_f32_16x16x32_bf16 v[102:105], v[162:165], v[180:183], v[102:105]
	v_mfma_f32_16x16x32_bf16 v[106:109], v[150:153], v[184:187], v[106:109]
	v_mfma_f32_16x16x32_bf16 v[106:109], v[154:157], v[192:195], v[106:109]
	v_mfma_f32_16x16x32_bf16 v[110:113], v[158:161], v[184:187], v[110:113]
	v_mfma_f32_16x16x32_bf16 v[110:113], v[162:165], v[192:195], v[110:113]
	v_mfma_f32_16x16x32_bf16 v[114:117], v[150:153], v[196:199], v[114:117]
	v_mfma_f32_16x16x32_bf16 v[114:117], v[154:157], v[200:203], v[114:117]
	v_mfma_f32_16x16x32_bf16 v[118:121], v[158:161], v[196:199], v[118:121]
	v_mfma_f32_16x16x32_bf16 v[118:121], v[162:165], v[200:203], v[118:121]
	v_mfma_f32_16x16x32_bf16 v[122:125], v[150:153], v[204:207], v[122:125]
	v_mfma_f32_16x16x32_bf16 v[122:125], v[154:157], v[208:211], v[122:125]
	v_mfma_f32_16x16x32_bf16 v[126:129], v[158:161], v[204:207], v[126:129]
	v_mfma_f32_16x16x32_bf16 v[126:129], v[162:165], v[208:211], v[126:129]
	s_setprio 0
	s_barrier
	s_add_i32 s55, s55, 2
	s_add_u32 s40, s40, 0x100
	s_addc_u32 s41, s41, 0
	s_cmp_gt_u32 s55, 29
	s_cbranch_scc0 .LBB0_685
	s_and_b64 vcc, exec, s[18:19]
	s_cbranch_vccz .LBB0_688
	s_barrier

.LBB0_755:
	s_add_u32 s6, s4, 0x100
	s_addc_u32 s7, s5, 0
	s_add_i32 s52, 0, 0x10000
	s_cmpk_eq_i32 s51, 0x54
	s_cselect_b32 s29, s23, s7
	s_cselect_b32 s28, s22, s6
	s_cselect_b32 s31, s27, s50
	s_cselect_b32 s30, s26, s33
	s_add_i32 s53, 0, 0x14000
	v_add_u32_e32 v142, s52, v242
	v_add_u32_e32 v158, s53, v242
	ds_read_b128 v[130:133], v142
	ds_read_b128 v[134:137], v142 offset:1024
	ds_read_b128 v[138:141], v142 offset:2048
	ds_read_b128 v[142:145], v142 offset:3072
	ds_read_b128 v[146:149], v158
	ds_read_b128 v[150:153], v158 offset:1024
	ds_read_b128 v[154:157], v158 offset:2048
	ds_read_b128 v[158:161], v158 offset:3072
	v_lshl_add_u64 v[194:195], s[4:5], 0, v[202:203]
	s_add_i32 m0, s36, 0xc000
	ds_read_b128 v[162:165], v243
	ds_read_b128 v[166:169], v243 offset:1024
	ds_read_b128 v[170:173], v243 offset:2048
	ds_read_b128 v[174:177], v243 offset:3072
	ds_read_b128 v[178:181], v243 offset:4096
	ds_read_b128 v[182:185], v243 offset:5120
	ds_read_b128 v[186:189], v243 offset:6144
	ds_read_b128 v[190:193], v243 offset:7168
	global_load_lds_dwordx4 v[194:195], off
	v_lshl_add_u64 v[194:195], s[4:5], 0, v[204:205]
	s_add_i32 m0, s36, 0xe000
	s_nop 0
	global_load_lds_dwordx4 v[194:195], off
	s_waitcnt vmcnt(8)
	s_waitcnt lgkmcnt(0)
	s_barrier
	s_setprio 1
	s_waitcnt lgkmcnt(0)
	v_mfma_f32_16x16x32_bf16 v[126:129], v[130:133], v[162:165], v[126:129]
	v_mfma_f32_16x16x32_bf16 v[126:129], v[134:137], v[166:169], v[126:129]
	v_mfma_f32_16x16x32_bf16 v[122:125], v[138:141], v[162:165], v[122:125]
	v_mfma_f32_16x16x32_bf16 v[122:125], v[142:145], v[166:169], v[122:125]
	v_mfma_f32_16x16x32_bf16 v[110:113], v[130:133], v[170:173], v[110:113]
	v_mfma_f32_16x16x32_bf16 v[110:113], v[134:137], v[174:177], v[110:113]
	v_mfma_f32_16x16x32_bf16 v[106:109], v[138:141], v[170:173], v[106:109]
	v_mfma_f32_16x16x32_bf16 v[106:109], v[142:145], v[174:177], v[106:109]
	v_mfma_f32_16x16x32_bf16 v[94:97], v[130:133], v[178:181], v[94:97]
	v_mfma_f32_16x16x32_bf16 v[94:97], v[134:137], v[182:185], v[94:97]
	v_mfma_f32_16x16x32_bf16 v[90:93], v[138:141], v[178:181], v[90:93]
	v_mfma_f32_16x16x32_bf16 v[90:93], v[142:145], v[182:185], v[90:93]
	v_mfma_f32_16x16x32_bf16 v[78:81], v[130:133], v[186:189], v[78:81]
	v_mfma_f32_16x16x32_bf16 v[78:81], v[134:137], v[190:193], v[78:81]
	v_mfma_f32_16x16x32_bf16 v[74:77], v[138:141], v[186:189], v[74:77]
	v_mfma_f32_16x16x32_bf16 v[74:77], v[142:145], v[190:193], v[74:77]
	s_setprio 0
	s_setprio 1
	v_mfma_f32_16x16x32_bf16 v[118:121], v[146:149], v[162:165], v[118:121]
	v_mfma_f32_16x16x32_bf16 v[118:121], v[150:153], v[166:169], v[118:121]
	v_mfma_f32_16x16x32_bf16 v[114:117], v[154:157], v[162:165], v[114:117]
	v_mfma_f32_16x16x32_bf16 v[114:117], v[158:161], v[166:169], v[114:117]
	v_mfma_f32_16x16x32_bf16 v[102:105], v[146:149], v[170:173], v[102:105]
	v_mfma_f32_16x16x32_bf16 v[102:105], v[150:153], v[174:177], v[102:105]
	v_mfma_f32_16x16x32_bf16 v[98:101], v[154:157], v[170:173], v[98:101]
	v_mfma_f32_16x16x32_bf16 v[98:101], v[158:161], v[174:177], v[98:101]
	v_mfma_f32_16x16x32_bf16 v[86:89], v[146:149], v[178:181], v[86:89]
	v_mfma_f32_16x16x32_bf16 v[86:89], v[150:153], v[182:185], v[86:89]
	v_mfma_f32_16x16x32_bf16 v[82:85], v[154:157], v[178:181], v[82:85]
	v_mfma_f32_16x16x32_bf16 v[82:85], v[158:161], v[182:185], v[82:85]
	v_mfma_f32_16x16x32_bf16 v[70:73], v[146:149], v[186:189], v[70:73]
	v_mfma_f32_16x16x32_bf16 v[70:73], v[150:153], v[190:193], v[70:73]
	v_mfma_f32_16x16x32_bf16 v[66:69], v[154:157], v[186:189], v[66:69]
	v_mfma_f32_16x16x32_bf16 v[66:69], v[158:161], v[190:193], v[66:69]
	s_setprio 0
	s_barrier
	s_add_i32 s4, s52, s1
	v_lshl_add_u64 v[194:195], s[30:31], 0, v[32:33]
	s_mov_b32 m0, s4
	ds_read_b128 v[162:165], v243 offset:16384
	ds_read_b128 v[166:169], v243 offset:17408
	ds_read_b128 v[170:173], v243 offset:18432
	ds_read_b128 v[174:177], v243 offset:19456
	ds_read_b128 v[178:181], v243 offset:20480
	ds_read_b128 v[182:185], v243 offset:21504
	ds_read_b128 v[186:189], v243 offset:22528
	ds_read_b128 v[190:193], v243 offset:23552
	global_load_lds_dwordx4 v[194:195], off
	s_add_i32 m0, s4, 0x2000
	s_add_u32 s4, s30, 0x160000
	v_lshl_add_u64 v[206:207], s[30:31], 0, v[200:201]
	s_addc_u32 s5, s31, 0
	s_add_i32 s52, s53, s1
	global_load_lds_dwordx4 v[206:207], off
	v_lshl_add_u64 v[208:209], s[4:5], 0, v[32:33]
	s_mov_b32 m0, s52
	v_lshl_add_u64 v[210:211], s[28:29], 0, v[198:199]
	global_load_lds_dwordx4 v[208:209], off
	v_lshl_add_u64 v[208:209], s[4:5], 0, v[200:201]
	s_add_i32 m0, s52, 0x2000
	s_nop 0
	global_load_lds_dwordx4 v[208:209], off
	v_lshl_add_u64 v[208:209], s[28:29], 0, v[196:197]
	s_mov_b32 m0, s36
	s_nop 0
	global_load_lds_dwordx4 v[208:209], off
	s_mov_b32 m0, s38
	s_nop 0
	global_load_lds_dwordx4 v[210:211], off
	s_waitcnt vmcnt(8)
	s_waitcnt lgkmcnt(0)
	s_barrier
	s_setprio 1
	s_waitcnt lgkmcnt(0)
	v_mfma_f32_16x16x32_bf16 v[62:65], v[130:133], v[162:165], v[62:65]
	v_mfma_f32_16x16x32_bf16 v[62:65], v[134:137], v[166:169], v[62:65]
	v_mfma_f32_16x16x32_bf16 v[58:61], v[138:141], v[162:165], v[58:61]
	v_mfma_f32_16x16x32_bf16 v[58:61], v[142:145], v[166:169], v[58:61]
	v_mfma_f32_16x16x32_bf16 v[46:49], v[130:133], v[170:173], v[46:49]
	v_mfma_f32_16x16x32_bf16 v[46:49], v[134:137], v[174:177], v[46:49]
	v_mfma_f32_16x16x32_bf16 v[42:45], v[138:141], v[170:173], v[42:45]
	v_mfma_f32_16x16x32_bf16 v[42:45], v[142:145], v[174:177], v[42:45]
	v_mfma_f32_16x16x32_bf16 v[28:31], v[130:133], v[178:181], v[28:31]
	v_mfma_f32_16x16x32_bf16 v[28:31], v[134:137], v[182:185], v[28:31]
	v_mfma_f32_16x16x32_bf16 v[24:27], v[138:141], v[178:181], v[24:27]
	v_mfma_f32_16x16x32_bf16 v[24:27], v[142:145], v[182:185], v[24:27]
	v_mfma_f32_16x16x32_bf16 v[12:15], v[130:133], v[186:189], v[12:15]
	v_mfma_f32_16x16x32_bf16 v[12:15], v[134:137], v[190:193], v[12:15]
	v_mfma_f32_16x16x32_bf16 v[8:11], v[138:141], v[186:189], v[8:11]
	v_mfma_f32_16x16x32_bf16 v[8:11], v[142:145], v[190:193], v[8:11]
	s_setprio 0
	s_setprio 1
	v_mfma_f32_16x16x32_bf16 v[54:57], v[146:149], v[162:165], v[54:57]
	v_mfma_f32_16x16x32_bf16 v[54:57], v[150:153], v[166:169], v[54:57]
	v_mfma_f32_16x16x32_bf16 v[50:53], v[154:157], v[162:165], v[50:53]
	v_mfma_f32_16x16x32_bf16 v[50:53], v[158:161], v[166:169], v[50:53]
	v_mfma_f32_16x16x32_bf16 v[38:41], v[146:149], v[170:173], v[38:41]
	v_mfma_f32_16x16x32_bf16 v[38:41], v[150:153], v[174:177], v[38:41]
	v_mfma_f32_16x16x32_bf16 v[34:37], v[154:157], v[170:173], v[34:37]
	v_mfma_f32_16x16x32_bf16 v[34:37], v[158:161], v[174:177], v[34:37]
	v_mfma_f32_16x16x32_bf16 v[20:23], v[146:149], v[178:181], v[20:23]
	v_mfma_f32_16x16x32_bf16 v[20:23], v[150:153], v[182:185], v[20:23]
	v_mfma_f32_16x16x32_bf16 v[16:19], v[154:157], v[178:181], v[16:19]
	v_mfma_f32_16x16x32_bf16 v[16:19], v[158:161], v[182:185], v[16:19]
	v_mfma_f32_16x16x32_bf16 v[4:7], v[146:149], v[186:189], v[4:7]
	v_mfma_f32_16x16x32_bf16 v[4:7], v[150:153], v[190:193], v[4:7]
	v_mfma_f32_16x16x32_bf16 v[0:3], v[154:157], v[186:189], v[0:3]
	v_mfma_f32_16x16x32_bf16 v[0:3], v[158:161], v[190:193], v[0:3]
	s_setprio 0
	s_barrier
	s_add_i32 s52, 0, 0x18000
	s_add_i32 s53, 0, 0x1c000
	v_add_u32_e32 v142, s52, v242
	v_add_u32_e32 v158, s53, v242
	ds_read_b128 v[130:133], v142
	ds_read_b128 v[134:137], v142 offset:1024
	ds_read_b128 v[138:141], v142 offset:2048
	ds_read_b128 v[142:145], v142 offset:3072
	ds_read_b128 v[146:149], v158
	ds_read_b128 v[150:153], v158 offset:1024
	ds_read_b128 v[154:157], v158 offset:2048
	ds_read_b128 v[158:161], v158 offset:3072
	s_add_u32 s4, s28, 0x160000
	s_addc_u32 s5, s29, 0
	s_mov_b32 m0, s39
	v_lshl_add_u64 v[212:213], s[4:5], 0, v[196:197]
	ds_read_b128 v[162:165], v243 offset:32768
	ds_read_b128 v[166:169], v243 offset:33792
	ds_read_b128 v[170:173], v243 offset:34816
	ds_read_b128 v[174:177], v243 offset:35840
	ds_read_b128 v[178:181], v243 offset:36864
	ds_read_b128 v[182:185], v243 offset:37888
	ds_read_b128 v[186:189], v243 offset:38912
	ds_read_b128 v[190:193], v243 offset:39936
	global_load_lds_dwordx4 v[212:213], off
	v_lshl_add_u64 v[212:213], s[4:5], 0, v[198:199]
	s_mov_b32 m0, s42
	s_nop 0
	global_load_lds_dwordx4 v[212:213], off
	s_waitcnt vmcnt(8)
	s_waitcnt lgkmcnt(0)
	s_barrier
	s_setprio 1
	s_waitcnt lgkmcnt(0)
	v_mfma_f32_16x16x32_bf16 v[126:129], v[130:133], v[162:165], v[126:129]
	v_mfma_f32_16x16x32_bf16 v[126:129], v[134:137], v[166:169], v[126:129]
	v_mfma_f32_16x16x32_bf16 v[122:125], v[138:141], v[162:165], v[122:125]
	v_mfma_f32_16x16x32_bf16 v[122:125], v[142:145], v[166:169], v[122:125]
	v_mfma_f32_16x16x32_bf16 v[110:113], v[130:133], v[170:173], v[110:113]
	v_mfma_f32_16x16x32_bf16 v[110:113], v[134:137], v[174:177], v[110:113]
	v_mfma_f32_16x16x32_bf16 v[106:109], v[138:141], v[170:173], v[106:109]
	v_mfma_f32_16x16x32_bf16 v[106:109], v[142:145], v[174:177], v[106:109]
	v_mfma_f32_16x16x32_bf16 v[94:97], v[130:133], v[178:181], v[94:97]
	v_mfma_f32_16x16x32_bf16 v[94:97], v[134:137], v[182:185], v[94:97]
	v_mfma_f32_16x16x32_bf16 v[90:93], v[138:141], v[178:181], v[90:93]
	v_mfma_f32_16x16x32_bf16 v[90:93], v[142:145], v[182:185], v[90:93]
	v_mfma_f32_16x16x32_bf16 v[78:81], v[130:133], v[186:189], v[78:81]
	v_mfma_f32_16x16x32_bf16 v[78:81], v[134:137], v[190:193], v[78:81]
	v_mfma_f32_16x16x32_bf16 v[74:77], v[138:141], v[186:189], v[74:77]
	v_mfma_f32_16x16x32_bf16 v[74:77], v[142:145], v[190:193], v[74:77]
	s_setprio 0
	s_setprio 1
	v_mfma_f32_16x16x32_bf16 v[118:121], v[146:149], v[162:165], v[118:121]
	v_mfma_f32_16x16x32_bf16 v[118:121], v[150:153], v[166:169], v[118:121]
	v_mfma_f32_16x16x32_bf16 v[114:117], v[154:157], v[162:165], v[114:117]
	v_mfma_f32_16x16x32_bf16 v[114:117], v[158:161], v[166:169], v[114:117]
	v_mfma_f32_16x16x32_bf16 v[102:105], v[146:149], v[170:173], v[102:105]
	v_mfma_f32_16x16x32_bf16 v[102:105], v[150:153], v[174:177], v[102:105]
	v_mfma_f32_16x16x32_bf16 v[98:101], v[154:157], v[170:173], v[98:101]
	v_mfma_f32_16x16x32_bf16 v[98:101], v[158:161], v[174:177], v[98:101]
	v_mfma_f32_16x16x32_bf16 v[86:89], v[146:149], v[178:181], v[86:89]
	v_mfma_f32_16x16x32_bf16 v[86:89], v[150:153], v[182:185], v[86:89]
	v_mfma_f32_16x16x32_bf16 v[82:85], v[154:157], v[178:181], v[82:85]
	v_mfma_f32_16x16x32_bf16 v[82:85], v[158:161], v[182:185], v[82:85]
	v_mfma_f32_16x16x32_bf16 v[70:73], v[146:149], v[186:189], v[70:73]
	v_mfma_f32_16x16x32_bf16 v[70:73], v[150:153], v[190:193], v[70:73]
	v_mfma_f32_16x16x32_bf16 v[66:69], v[154:157], v[186:189], v[66:69]
	v_mfma_f32_16x16x32_bf16 v[66:69], v[158:161], v[190:193], v[66:69]
	s_setprio 0
	s_barrier
	s_add_i32 s4, s52, s1
	v_lshl_add_u64 v[194:195], v[194:195], 0, s[34:35]
	s_mov_b32 m0, s4
	ds_read_b128 v[162:165], v243 offset:49152
	ds_read_b128 v[166:169], v243 offset:50176
	ds_read_b128 v[170:173], v243 offset:51200
	ds_read_b128 v[174:177], v243 offset:52224
	ds_read_b128 v[178:181], v243 offset:53248
	ds_read_b128 v[182:185], v243 offset:54272
	ds_read_b128 v[186:189], v243 offset:55296
	ds_read_b128 v[190:193], v243 offset:56320
	global_load_lds_dwordx4 v[194:195], off
	s_add_i32 m0, s4, 0x2000
	s_add_u32 s4, s30, 0x160080
	v_lshl_add_u64 v[194:195], v[206:207], 0, s[34:35]
	s_addc_u32 s5, s31, 0
	s_add_i32 s28, s53, s1
	global_load_lds_dwordx4 v[194:195], off
	v_lshl_add_u64 v[194:195], s[4:5], 0, v[32:33]
	s_mov_b32 m0, s28
	s_nop 0
	global_load_lds_dwordx4 v[194:195], off
	v_lshl_add_u64 v[194:195], s[4:5], 0, v[200:201]
	s_add_i32 m0, s28, 0x2000
	s_nop 0
	global_load_lds_dwordx4 v[194:195], off
	v_lshl_add_u64 v[194:195], v[208:209], 0, s[34:35]
	s_mov_b32 m0, s44
	s_nop 0
	global_load_lds_dwordx4 v[194:195], off
	v_lshl_add_u64 v[194:195], v[210:211], 0, s[34:35]
	s_mov_b32 m0, s45
	s_nop 0
	global_load_lds_dwordx4 v[194:195], off
	s_waitcnt vmcnt(8)
	s_waitcnt lgkmcnt(0)
	s_barrier
	s_setprio 1
	s_waitcnt lgkmcnt(0)
	v_mfma_f32_16x16x32_bf16 v[62:65], v[130:133], v[162:165], v[62:65]
	v_mfma_f32_16x16x32_bf16 v[62:65], v[134:137], v[166:169], v[62:65]
	v_mfma_f32_16x16x32_bf16 v[58:61], v[138:141], v[162:165], v[58:61]
	v_mfma_f32_16x16x32_bf16 v[58:61], v[142:145], v[166:169], v[58:61]
	v_mfma_f32_16x16x32_bf16 v[46:49], v[130:133], v[170:173], v[46:49]
	v_mfma_f32_16x16x32_bf16 v[46:49], v[134:137], v[174:177], v[46:49]
	v_mfma_f32_16x16x32_bf16 v[42:45], v[138:141], v[170:173], v[42:45]
	v_mfma_f32_16x16x32_bf16 v[42:45], v[142:145], v[174:177], v[42:45]
	v_mfma_f32_16x16x32_bf16 v[28:31], v[130:133], v[178:181], v[28:31]
	v_mfma_f32_16x16x32_bf16 v[28:31], v[134:137], v[182:185], v[28:31]
	v_mfma_f32_16x16x32_bf16 v[24:27], v[138:141], v[178:181], v[24:27]
	v_mfma_f32_16x16x32_bf16 v[24:27], v[142:145], v[182:185], v[24:27]
	v_mfma_f32_16x16x32_bf16 v[12:15], v[130:133], v[186:189], v[12:15]
	v_mfma_f32_16x16x32_bf16 v[12:15], v[134:137], v[190:193], v[12:15]
	v_mfma_f32_16x16x32_bf16 v[8:11], v[138:141], v[186:189], v[8:11]
	v_mfma_f32_16x16x32_bf16 v[8:11], v[142:145], v[190:193], v[8:11]
	s_setprio 0
	s_setprio 1
	v_mfma_f32_16x16x32_bf16 v[54:57], v[146:149], v[162:165], v[54:57]
	v_mfma_f32_16x16x32_bf16 v[54:57], v[150:153], v[166:169], v[54:57]
	v_mfma_f32_16x16x32_bf16 v[50:53], v[154:157], v[162:165], v[50:53]
	v_mfma_f32_16x16x32_bf16 v[50:53], v[158:161], v[166:169], v[50:53]
	v_mfma_f32_16x16x32_bf16 v[38:41], v[146:149], v[170:173], v[38:41]
	v_mfma_f32_16x16x32_bf16 v[38:41], v[150:153], v[174:177], v[38:41]
	v_mfma_f32_16x16x32_bf16 v[34:37], v[154:157], v[170:173], v[34:37]
	v_mfma_f32_16x16x32_bf16 v[34:37], v[158:161], v[174:177], v[34:37]
	v_mfma_f32_16x16x32_bf16 v[20:23], v[146:149], v[178:181], v[20:23]
	v_mfma_f32_16x16x32_bf16 v[20:23], v[150:153], v[182:185], v[20:23]
	v_mfma_f32_16x16x32_bf16 v[16:19], v[154:157], v[178:181], v[16:19]
	v_mfma_f32_16x16x32_bf16 v[16:19], v[158:161], v[182:185], v[16:19]
	v_mfma_f32_16x16x32_bf16 v[4:7], v[146:149], v[186:189], v[4:7]
	v_mfma_f32_16x16x32_bf16 v[4:7], v[150:153], v[190:193], v[4:7]
	v_mfma_f32_16x16x32_bf16 v[0:3], v[154:157], v[186:189], v[0:3]
	v_mfma_f32_16x16x32_bf16 v[0:3], v[158:161], v[190:193], v[0:3]
	s_setprio 0
	s_barrier
	s_add_i32 s51, s51, 2
	s_add_u32 s33, s33, 0x100
	s_addc_u32 s50, s50, 0
	s_cmpk_gt_u32 s51, 0x55
	s_mov_b64 s[4:5], s[6:7]
	s_cbranch_scc0 .LBB0_755
	s_and_b64 vcc, exec, s[18:19]
	s_cbranch_vccz .LBB0_758
	s_barrier

.LBB0_888:
	s_add_u32 s38, s16, s30
	s_addc_u32 s39, s17, s31
	s_add_u32 s38, s38, 0x100
	s_addc_u32 s39, s39, 0
	s_add_u32 s54, s50, s30
	s_addc_u32 s55, s51, s31
	s_add_i32 s56, 0, 0x10000
	s_cmpk_eq_i32 s30, 0xf00
	s_cselect_b32 s41, s29, s39
	s_cselect_b32 s40, s28, s38
	s_cselect_b32 s39, s21, s55
	s_cselect_b32 s38, s52, s54
	s_add_i32 s57, 0, 0x14000
	v_add_u32_e32 v146, s56, v178
	v_add_u32_e32 v172, s57, v178
	ds_read_b128 v[134:137], v146
	ds_read_b128 v[138:141], v146 offset:1024
	ds_read_b128 v[142:145], v146 offset:2048
	ds_read_b128 v[146:149], v146 offset:3072
	ds_read_b128 v[150:153], v172
	ds_read_b128 v[154:157], v172 offset:1024
	ds_read_b128 v[158:161], v172 offset:2048
	ds_read_b128 v[172:175], v172 offset:3072
	v_lshl_add_u64 v[212:213], v[130:131], 0, s[30:31]
	s_add_i32 m0, s24, 0xc000
	ds_read_b128 v[180:183], v179
	ds_read_b128 v[184:187], v179 offset:1024
	ds_read_b128 v[188:191], v179 offset:2048
	ds_read_b128 v[192:195], v179 offset:3072
	ds_read_b128 v[196:199], v179 offset:4096
	ds_read_b128 v[200:203], v179 offset:5120
	ds_read_b128 v[204:207], v179 offset:6144
	ds_read_b128 v[208:211], v179 offset:7168
	global_load_lds_dwordx4 v[212:213], off
	v_lshl_add_u64 v[212:213], v[132:133], 0, s[30:31]
	s_add_i32 m0, s24, 0xe000
	s_nop 0
	global_load_lds_dwordx4 v[212:213], off
	s_waitcnt vmcnt(8)
	s_waitcnt lgkmcnt(0)
	s_barrier
	s_setprio 1
	s_waitcnt lgkmcnt(0)
	v_mfma_f32_16x16x32_bf16 v[82:85], v[134:137], v[180:183], v[82:85]
	v_mfma_f32_16x16x32_bf16 v[82:85], v[138:141], v[184:187], v[82:85]
	v_mfma_f32_16x16x32_bf16 v[78:81], v[142:145], v[180:183], v[78:81]
	v_mfma_f32_16x16x32_bf16 v[78:81], v[146:149], v[184:187], v[78:81]
	v_mfma_f32_16x16x32_bf16 v[74:77], v[134:137], v[188:191], v[74:77]
	v_mfma_f32_16x16x32_bf16 v[74:77], v[138:141], v[192:195], v[74:77]
	v_mfma_f32_16x16x32_bf16 v[70:73], v[142:145], v[188:191], v[70:73]
	v_mfma_f32_16x16x32_bf16 v[70:73], v[146:149], v[192:195], v[70:73]
	v_mfma_f32_16x16x32_bf16 v[66:69], v[134:137], v[196:199], v[66:69]
	v_mfma_f32_16x16x32_bf16 v[66:69], v[138:141], v[200:203], v[66:69]
	v_mfma_f32_16x16x32_bf16 v[62:65], v[142:145], v[196:199], v[62:65]
	v_mfma_f32_16x16x32_bf16 v[62:65], v[146:149], v[200:203], v[62:65]
	v_mfma_f32_16x16x32_bf16 v[58:61], v[134:137], v[204:207], v[58:61]
	v_mfma_f32_16x16x32_bf16 v[58:61], v[138:141], v[208:211], v[58:61]
	v_mfma_f32_16x16x32_bf16 v[54:57], v[142:145], v[204:207], v[54:57]
	v_mfma_f32_16x16x32_bf16 v[54:57], v[146:149], v[208:211], v[54:57]
	s_setprio 0
	s_setprio 1
	v_mfma_f32_16x16x32_bf16 v[50:53], v[150:153], v[180:183], v[50:53]
	v_mfma_f32_16x16x32_bf16 v[50:53], v[154:157], v[184:187], v[50:53]
	v_mfma_f32_16x16x32_bf16 v[46:49], v[158:161], v[180:183], v[46:49]
	v_mfma_f32_16x16x32_bf16 v[46:49], v[172:175], v[184:187], v[46:49]
	v_mfma_f32_16x16x32_bf16 v[42:45], v[150:153], v[188:191], v[42:45]
	v_mfma_f32_16x16x32_bf16 v[42:45], v[154:157], v[192:195], v[42:45]
	v_mfma_f32_16x16x32_bf16 v[38:41], v[158:161], v[188:191], v[38:41]
	v_mfma_f32_16x16x32_bf16 v[38:41], v[172:175], v[192:195], v[38:41]
	v_mfma_f32_16x16x32_bf16 v[34:37], v[150:153], v[196:199], v[34:37]
	v_mfma_f32_16x16x32_bf16 v[34:37], v[154:157], v[200:203], v[34:37]
	v_mfma_f32_16x16x32_bf16 v[28:31], v[158:161], v[196:199], v[28:31]
	v_mfma_f32_16x16x32_bf16 v[28:31], v[172:175], v[200:203], v[28:31]
	v_mfma_f32_16x16x32_bf16 v[24:27], v[150:153], v[204:207], v[24:27]
	v_mfma_f32_16x16x32_bf16 v[24:27], v[154:157], v[208:211], v[24:27]
	v_mfma_f32_16x16x32_bf16 v[20:23], v[158:161], v[204:207], v[20:23]
	v_mfma_f32_16x16x32_bf16 v[20:23], v[172:175], v[208:211], v[20:23]
	s_setprio 0
	s_barrier
	s_add_i32 s54, s56, s13
	v_lshl_add_u64 v[212:213], s[38:39], 0, v[32:33]
	s_mov_b32 m0, s54
	ds_read_b128 v[180:183], v179 offset:16384
	ds_read_b128 v[184:187], v179 offset:17408
	ds_read_b128 v[188:191], v179 offset:18432
	ds_read_b128 v[192:195], v179 offset:19456
	ds_read_b128 v[196:199], v179 offset:20480
	ds_read_b128 v[200:203], v179 offset:21504
	ds_read_b128 v[204:207], v179 offset:22528
	ds_read_b128 v[208:211], v179 offset:23552
	global_load_lds_dwordx4 v[212:213], off
	s_add_i32 m0, s54, 0x2000
	s_add_u32 s54, s38, 0x80000
	v_lshl_add_u64 v[214:215], s[38:39], 0, v[166:167]
	s_addc_u32 s55, s39, 0
	s_add_i32 s56, s57, s13
	global_load_lds_dwordx4 v[214:215], off
	v_lshl_add_u64 v[216:217], s[54:55], 0, v[32:33]
	s_mov_b32 m0, s56
	v_lshl_add_u64 v[220:221], s[40:41], 0, v[164:165]
	global_load_lds_dwordx4 v[216:217], off
	v_lshl_add_u64 v[216:217], s[54:55], 0, v[166:167]
	s_add_i32 m0, s56, 0x2000
	s_nop 0
	global_load_lds_dwordx4 v[216:217], off
	v_lshl_add_u64 v[216:217], s[40:41], 0, v[162:163]
	s_mov_b32 m0, s24
	s_nop 0
	global_load_lds_dwordx4 v[216:217], off
	s_mov_b32 m0, s25
	s_nop 0
	global_load_lds_dwordx4 v[220:221], off
	s_waitcnt vmcnt(8)
	s_waitcnt lgkmcnt(0)
	s_barrier
	s_setprio 1
	s_waitcnt lgkmcnt(0)
	v_mfma_f32_16x16x32_bf16 v[16:19], v[134:137], v[180:183], v[16:19]
	v_mfma_f32_16x16x32_bf16 v[16:19], v[138:141], v[184:187], v[16:19]
	v_mfma_f32_16x16x32_bf16 v[12:15], v[142:145], v[180:183], v[12:15]
	v_mfma_f32_16x16x32_bf16 v[12:15], v[146:149], v[184:187], v[12:15]
	v_mfma_f32_16x16x32_bf16 v[8:11], v[134:137], v[188:191], v[8:11]
	v_mfma_f32_16x16x32_bf16 v[8:11], v[138:141], v[192:195], v[8:11]
	v_mfma_f32_16x16x32_bf16 v[4:7], v[142:145], v[188:191], v[4:7]
	v_mfma_f32_16x16x32_bf16 v[4:7], v[146:149], v[192:195], v[4:7]
	v_mfma_f32_16x16x32_bf16 v[0:3], v[134:137], v[196:199], v[0:3]
	v_mfma_f32_16x16x32_bf16 v[0:3], v[138:141], v[200:203], v[0:3]
	v_mfma_f32_16x16x32_bf16 v[86:89], v[142:145], v[196:199], v[86:89]
	v_mfma_f32_16x16x32_bf16 v[86:89], v[146:149], v[200:203], v[86:89]
	v_mfma_f32_16x16x32_bf16 v[90:93], v[134:137], v[204:207], v[90:93]
	v_mfma_f32_16x16x32_bf16 v[90:93], v[138:141], v[208:211], v[90:93]
	v_mfma_f32_16x16x32_bf16 v[94:97], v[142:145], v[204:207], v[94:97]
	v_mfma_f32_16x16x32_bf16 v[94:97], v[146:149], v[208:211], v[94:97]
	s_setprio 0
	s_setprio 1
	v_mfma_f32_16x16x32_bf16 v[98:101], v[150:153], v[180:183], v[98:101]
	v_mfma_f32_16x16x32_bf16 v[98:101], v[154:157], v[184:187], v[98:101]
	v_mfma_f32_16x16x32_bf16 v[102:105], v[158:161], v[180:183], v[102:105]
	v_mfma_f32_16x16x32_bf16 v[102:105], v[172:175], v[184:187], v[102:105]
	v_mfma_f32_16x16x32_bf16 v[106:109], v[150:153], v[188:191], v[106:109]
	v_mfma_f32_16x16x32_bf16 v[106:109], v[154:157], v[192:195], v[106:109]
	v_mfma_f32_16x16x32_bf16 v[110:113], v[158:161], v[188:191], v[110:113]
	v_mfma_f32_16x16x32_bf16 v[110:113], v[172:175], v[192:195], v[110:113]
	v_mfma_f32_16x16x32_bf16 v[114:117], v[150:153], v[196:199], v[114:117]
	v_mfma_f32_16x16x32_bf16 v[114:117], v[154:157], v[200:203], v[114:117]
	v_mfma_f32_16x16x32_bf16 v[118:121], v[158:161], v[196:199], v[118:121]
	v_mfma_f32_16x16x32_bf16 v[118:121], v[172:175], v[200:203], v[118:121]
	v_mfma_f32_16x16x32_bf16 v[122:125], v[150:153], v[204:207], v[122:125]
	v_mfma_f32_16x16x32_bf16 v[122:125], v[154:157], v[208:211], v[122:125]
	v_mfma_f32_16x16x32_bf16 v[126:129], v[158:161], v[204:207], v[126:129]
	v_mfma_f32_16x16x32_bf16 v[126:129], v[172:175], v[208:211], v[126:129]
	s_setprio 0
	s_barrier
	s_add_i32 s54, 0, 0x18000
	s_add_i32 s55, 0, 0x1c000
	v_add_u32_e32 v146, s54, v178
	v_add_u32_e32 v172, s55, v178
	ds_read_b128 v[134:137], v146
	ds_read_b128 v[138:141], v146 offset:1024
	ds_read_b128 v[142:145], v146 offset:2048
	ds_read_b128 v[146:149], v146 offset:3072
	ds_read_b128 v[150:153], v172
	ds_read_b128 v[154:157], v172 offset:1024
	ds_read_b128 v[158:161], v172 offset:2048
	ds_read_b128 v[172:175], v172 offset:3072
	s_add_u32 s40, s40, 0x80000
	s_addc_u32 s41, s41, 0
	s_mov_b32 m0, s33
	v_lshl_add_u64 v[222:223], s[40:41], 0, v[162:163]
	ds_read_b128 v[180:183], v179 offset:32768
	ds_read_b128 v[184:187], v179 offset:33792
	ds_read_b128 v[188:191], v179 offset:34816
	ds_read_b128 v[192:195], v179 offset:35840
	ds_read_b128 v[196:199], v179 offset:36864
	ds_read_b128 v[200:203], v179 offset:37888
	ds_read_b128 v[204:207], v179 offset:38912
	ds_read_b128 v[208:211], v179 offset:39936
	global_load_lds_dwordx4 v[222:223], off
	v_lshl_add_u64 v[222:223], s[40:41], 0, v[164:165]
	s_mov_b32 m0, s36
	s_nop 0
	global_load_lds_dwordx4 v[222:223], off
	s_waitcnt vmcnt(8)
	s_waitcnt lgkmcnt(0)
	s_barrier
	s_setprio 1
	s_waitcnt lgkmcnt(0)
	v_mfma_f32_16x16x32_bf16 v[82:85], v[134:137], v[180:183], v[82:85]
	v_mfma_f32_16x16x32_bf16 v[82:85], v[138:141], v[184:187], v[82:85]
	v_mfma_f32_16x16x32_bf16 v[78:81], v[142:145], v[180:183], v[78:81]
	v_mfma_f32_16x16x32_bf16 v[78:81], v[146:149], v[184:187], v[78:81]
	v_mfma_f32_16x16x32_bf16 v[74:77], v[134:137], v[188:191], v[74:77]
	v_mfma_f32_16x16x32_bf16 v[74:77], v[138:141], v[192:195], v[74:77]
	v_mfma_f32_16x16x32_bf16 v[70:73], v[142:145], v[188:191], v[70:73]
	v_mfma_f32_16x16x32_bf16 v[70:73], v[146:149], v[192:195], v[70:73]
	v_mfma_f32_16x16x32_bf16 v[66:69], v[134:137], v[196:199], v[66:69]
	v_mfma_f32_16x16x32_bf16 v[66:69], v[138:141], v[200:203], v[66:69]
	v_mfma_f32_16x16x32_bf16 v[62:65], v[142:145], v[196:199], v[62:65]
	v_mfma_f32_16x16x32_bf16 v[62:65], v[146:149], v[200:203], v[62:65]
	v_mfma_f32_16x16x32_bf16 v[58:61], v[134:137], v[204:207], v[58:61]
	v_mfma_f32_16x16x32_bf16 v[58:61], v[138:141], v[208:211], v[58:61]
	v_mfma_f32_16x16x32_bf16 v[54:57], v[142:145], v[204:207], v[54:57]
	v_mfma_f32_16x16x32_bf16 v[54:57], v[146:149], v[208:211], v[54:57]
	s_setprio 0
	s_setprio 1
	v_mfma_f32_16x16x32_bf16 v[50:53], v[150:153], v[180:183], v[50:53]
	v_mfma_f32_16x16x32_bf16 v[50:53], v[154:157], v[184:187], v[50:53]
	v_mfma_f32_16x16x32_bf16 v[46:49], v[158:161], v[180:183], v[46:49]
	v_mfma_f32_16x16x32_bf16 v[46:49], v[172:175], v[184:187], v[46:49]
	v_mfma_f32_16x16x32_bf16 v[42:45], v[150:153], v[188:191], v[42:45]
	v_mfma_f32_16x16x32_bf16 v[42:45], v[154:157], v[192:195], v[42:45]
	v_mfma_f32_16x16x32_bf16 v[38:41], v[158:161], v[188:191], v[38:41]
	v_mfma_f32_16x16x32_bf16 v[38:41], v[172:175], v[192:195], v[38:41]
	v_mfma_f32_16x16x32_bf16 v[34:37], v[150:153], v[196:199], v[34:37]
	v_mfma_f32_16x16x32_bf16 v[34:37], v[154:157], v[200:203], v[34:37]
	v_mfma_f32_16x16x32_bf16 v[28:31], v[158:161], v[196:199], v[28:31]
	v_mfma_f32_16x16x32_bf16 v[28:31], v[172:175], v[200:203], v[28:31]
	v_mfma_f32_16x16x32_bf16 v[24:27], v[150:153], v[204:207], v[24:27]
	v_mfma_f32_16x16x32_bf16 v[24:27], v[154:157], v[208:211], v[24:27]
	v_mfma_f32_16x16x32_bf16 v[20:23], v[158:161], v[204:207], v[20:23]
	v_mfma_f32_16x16x32_bf16 v[20:23], v[172:175], v[208:211], v[20:23]
	s_setprio 0
	s_barrier
	s_add_i32 s40, s54, s13
	v_lshl_add_u64 v[212:213], v[212:213], 0, s[34:35]
	s_mov_b32 m0, s40
	ds_read_b128 v[180:183], v179 offset:49152
	ds_read_b128 v[184:187], v179 offset:50176
	ds_read_b128 v[188:191], v179 offset:51200
	ds_read_b128 v[192:195], v179 offset:52224
	ds_read_b128 v[196:199], v179 offset:53248
	ds_read_b128 v[200:203], v179 offset:54272
	ds_read_b128 v[204:207], v179 offset:55296
	ds_read_b128 v[208:211], v179 offset:56320
	global_load_lds_dwordx4 v[212:213], off
	s_add_i32 m0, s40, 0x2000
	s_add_u32 s38, s38, 0x80080
	v_lshl_add_u64 v[212:213], v[214:215], 0, s[34:35]
	s_addc_u32 s39, s39, 0
	s_add_i32 s40, s55, s13
	global_load_lds_dwordx4 v[212:213], off
	v_lshl_add_u64 v[212:213], s[38:39], 0, v[32:33]
	s_mov_b32 m0, s40
	s_nop 0
	global_load_lds_dwordx4 v[212:213], off
	v_lshl_add_u64 v[212:213], s[38:39], 0, v[166:167]
	s_add_i32 m0, s40, 0x2000
	s_nop 0
	global_load_lds_dwordx4 v[212:213], off
	v_lshl_add_u64 v[212:213], v[216:217], 0, s[34:35]
	s_mov_b32 m0, s43
	s_nop 0
	global_load_lds_dwordx4 v[212:213], off
	v_lshl_add_u64 v[212:213], v[220:221], 0, s[34:35]
	s_mov_b32 m0, s44
	s_nop 0
	global_load_lds_dwordx4 v[212:213], off
	s_waitcnt vmcnt(8)
	s_waitcnt lgkmcnt(0)
	s_barrier
	s_setprio 1
	s_waitcnt lgkmcnt(0)
	v_mfma_f32_16x16x32_bf16 v[16:19], v[134:137], v[180:183], v[16:19]
	v_mfma_f32_16x16x32_bf16 v[16:19], v[138:141], v[184:187], v[16:19]
	v_mfma_f32_16x16x32_bf16 v[12:15], v[142:145], v[180:183], v[12:15]
	v_mfma_f32_16x16x32_bf16 v[12:15], v[146:149], v[184:187], v[12:15]
	v_mfma_f32_16x16x32_bf16 v[8:11], v[134:137], v[188:191], v[8:11]
	v_mfma_f32_16x16x32_bf16 v[8:11], v[138:141], v[192:195], v[8:11]
	v_mfma_f32_16x16x32_bf16 v[4:7], v[142:145], v[188:191], v[4:7]
	v_mfma_f32_16x16x32_bf16 v[4:7], v[146:149], v[192:195], v[4:7]
	v_mfma_f32_16x16x32_bf16 v[0:3], v[134:137], v[196:199], v[0:3]
	v_mfma_f32_16x16x32_bf16 v[0:3], v[138:141], v[200:203], v[0:3]
	v_mfma_f32_16x16x32_bf16 v[86:89], v[142:145], v[196:199], v[86:89]
	v_mfma_f32_16x16x32_bf16 v[86:89], v[146:149], v[200:203], v[86:89]
	v_mfma_f32_16x16x32_bf16 v[90:93], v[134:137], v[204:207], v[90:93]
	v_mfma_f32_16x16x32_bf16 v[90:93], v[138:141], v[208:211], v[90:93]
	v_mfma_f32_16x16x32_bf16 v[94:97], v[142:145], v[204:207], v[94:97]
	v_mfma_f32_16x16x32_bf16 v[94:97], v[146:149], v[208:211], v[94:97]
	s_setprio 0
	s_setprio 1
	v_mfma_f32_16x16x32_bf16 v[98:101], v[150:153], v[180:183], v[98:101]
	v_mfma_f32_16x16x32_bf16 v[98:101], v[154:157], v[184:187], v[98:101]
	v_mfma_f32_16x16x32_bf16 v[102:105], v[158:161], v[180:183], v[102:105]
	v_mfma_f32_16x16x32_bf16 v[102:105], v[172:175], v[184:187], v[102:105]
	v_mfma_f32_16x16x32_bf16 v[106:109], v[150:153], v[188:191], v[106:109]
	v_mfma_f32_16x16x32_bf16 v[106:109], v[154:157], v[192:195], v[106:109]
	v_mfma_f32_16x16x32_bf16 v[110:113], v[158:161], v[188:191], v[110:113]
	v_mfma_f32_16x16x32_bf16 v[110:113], v[172:175], v[192:195], v[110:113]
	v_mfma_f32_16x16x32_bf16 v[114:117], v[150:153], v[196:199], v[114:117]
	v_mfma_f32_16x16x32_bf16 v[114:117], v[154:157], v[200:203], v[114:117]
	v_mfma_f32_16x16x32_bf16 v[118:121], v[158:161], v[196:199], v[118:121]
	v_mfma_f32_16x16x32_bf16 v[118:121], v[172:175], v[200:203], v[118:121]
	v_mfma_f32_16x16x32_bf16 v[122:125], v[150:153], v[204:207], v[122:125]
	v_mfma_f32_16x16x32_bf16 v[122:125], v[154:157], v[208:211], v[122:125]
	v_mfma_f32_16x16x32_bf16 v[126:129], v[158:161], v[204:207], v[126:129]
	v_mfma_f32_16x16x32_bf16 v[126:129], v[172:175], v[208:211], v[126:129]
	s_setprio 0
	s_barrier
	s_add_i32 s53, s53, 2
	s_add_u32 s30, s30, 0x100
	s_addc_u32 s31, s31, 0
	s_cmp_gt_u32 s53, 29
	s_cbranch_scc0 .LBB0_888
	s_and_b64 vcc, exec, s[18:19]
	s_cbranch_vccz .LBB0_891
	s_barrier
